# v139 with the W_up warm-up moved from the out-projection phase entry to its epilogue start
# speedup vs baseline: 1.0096x; 1.0096x over previous
.LBB0_110:
	s_add_u32 s54, s52, 0xfff80080
	s_addc_u32 s55, s53, -1
	s_add_i32 s64, 0, 0x10000
	s_cmp_eq_u32 s63, 28
	s_cselect_b32 s57, s4, s55
	s_cselect_b32 s56, s5, s54
	s_cselect_b32 s55, s37, s62
	s_cselect_b32 s54, s43, s61
	s_add_i32 s66, 0, 0x14000
	v_add_u32_e32 v156, s64, v163
	v_add_u32_e32 v160, s66, v163
	ds_read_b128 v[134:137], v156
	ds_read_b128 v[138:141], v156 offset:1024
	ds_read_b128 v[152:155], v156 offset:2048
	ds_read_b128 v[156:159], v156 offset:3072
	ds_read_b128 v[166:169], v160
	ds_read_b128 v[170:173], v160 offset:1024
	ds_read_b128 v[174:177], v160 offset:2048
	ds_read_b128 v[178:181], v160 offset:3072
	v_lshl_add_u64 v[160:161], s[52:53], 0, v[150:151]
	s_add_i32 m0, s21, 0xc000
	ds_read_b128 v[182:185], v165
	ds_read_b128 v[186:189], v165 offset:1024
	ds_read_b128 v[198:201], v165 offset:2048
	ds_read_b128 v[202:205], v165 offset:3072
	ds_read_b128 v[206:209], v165 offset:4096
	ds_read_b128 v[210:213], v165 offset:5120
	ds_read_b128 v[214:217], v165 offset:6144
	ds_read_b128 v[236:239], v165 offset:7168
	global_load_lds_dwordx4 v[160:161], off
	v_lshl_add_u64 v[160:161], s[52:53], 0, v[148:149]
	s_add_i32 m0, s21, 0xe000
	s_nop 0
	global_load_lds_dwordx4 v[160:161], off
	s_waitcnt vmcnt(8)
	s_waitcnt lgkmcnt(0)
	s_barrier
	s_setprio 1
	s_waitcnt lgkmcnt(0)
	v_mfma_f32_16x16x32_bf16 v[130:133], v[134:137], v[182:185], v[130:133]
	v_mfma_f32_16x16x32_bf16 v[126:129], v[152:155], v[182:185], v[126:129]
	v_mfma_f32_16x16x32_bf16 v[114:117], v[134:137], v[198:201], v[114:117]
	v_mfma_f32_16x16x32_bf16 v[110:113], v[152:155], v[198:201], v[110:113]
	v_mfma_f32_16x16x32_bf16 v[98:101], v[134:137], v[206:209], v[98:101]
	v_mfma_f32_16x16x32_bf16 v[94:97], v[152:155], v[206:209], v[94:97]
	v_mfma_f32_16x16x32_bf16 v[82:85], v[134:137], v[214:217], v[82:85]
	v_mfma_f32_16x16x32_bf16 v[78:81], v[152:155], v[214:217], v[78:81]
	v_mfma_f32_16x16x32_bf16 v[130:133], v[138:141], v[186:189], v[130:133]
	v_mfma_f32_16x16x32_bf16 v[126:129], v[156:159], v[186:189], v[126:129]
	v_mfma_f32_16x16x32_bf16 v[114:117], v[138:141], v[202:205], v[114:117]
	v_mfma_f32_16x16x32_bf16 v[110:113], v[156:159], v[202:205], v[110:113]
	v_mfma_f32_16x16x32_bf16 v[98:101], v[138:141], v[210:213], v[98:101]
	v_mfma_f32_16x16x32_bf16 v[94:97], v[156:159], v[210:213], v[94:97]
	v_mfma_f32_16x16x32_bf16 v[82:85], v[138:141], v[236:239], v[82:85]
	v_mfma_f32_16x16x32_bf16 v[78:81], v[156:159], v[236:239], v[78:81]
	s_setprio 0
	s_setprio 1
	v_mfma_f32_16x16x32_bf16 v[122:125], v[166:169], v[182:185], v[122:125]
	v_mfma_f32_16x16x32_bf16 v[118:121], v[174:177], v[182:185], v[118:121]
	v_mfma_f32_16x16x32_bf16 v[106:109], v[166:169], v[198:201], v[106:109]
	v_mfma_f32_16x16x32_bf16 v[102:105], v[174:177], v[198:201], v[102:105]
	v_mfma_f32_16x16x32_bf16 v[90:93], v[166:169], v[206:209], v[90:93]
	v_mfma_f32_16x16x32_bf16 v[86:89], v[174:177], v[206:209], v[86:89]
	v_mfma_f32_16x16x32_bf16 v[74:77], v[166:169], v[214:217], v[74:77]
	v_mfma_f32_16x16x32_bf16 v[70:73], v[174:177], v[214:217], v[70:73]
	v_mfma_f32_16x16x32_bf16 v[122:125], v[170:173], v[186:189], v[122:125]
	v_mfma_f32_16x16x32_bf16 v[118:121], v[178:181], v[186:189], v[118:121]
	v_mfma_f32_16x16x32_bf16 v[106:109], v[170:173], v[202:205], v[106:109]
	v_mfma_f32_16x16x32_bf16 v[102:105], v[178:181], v[202:205], v[102:105]
	v_mfma_f32_16x16x32_bf16 v[90:93], v[170:173], v[210:213], v[90:93]
	v_mfma_f32_16x16x32_bf16 v[86:89], v[178:181], v[210:213], v[86:89]
	v_mfma_f32_16x16x32_bf16 v[74:77], v[170:173], v[236:239], v[74:77]
	v_mfma_f32_16x16x32_bf16 v[70:73], v[178:181], v[236:239], v[70:73]
	s_setprio 0
	s_barrier
	s_add_i32 s64, s64, s15
	v_lshl_add_u64 v[160:161], s[54:55], 0, v[190:191]
	s_mov_b32 m0, s64
	ds_read_b128 v[182:185], v165 offset:16384
	ds_read_b128 v[186:189], v165 offset:17408
	ds_read_b128 v[198:201], v165 offset:18432
	ds_read_b128 v[202:205], v165 offset:19456
	ds_read_b128 v[206:209], v165 offset:20480
	ds_read_b128 v[210:213], v165 offset:21504
	ds_read_b128 v[214:217], v165 offset:22528
	ds_read_b128 v[236:239], v165 offset:23552
	global_load_lds_dwordx4 v[160:161], off
	s_add_i32 m0, s64, 0x2000
	s_add_u32 s64, s54, 0x80000
	v_lshl_add_u64 v[218:219], s[54:55], 0, v[146:147]
	s_addc_u32 s65, s55, 0
	s_add_i32 s66, s66, s15
	global_load_lds_dwordx4 v[218:219], off
	v_lshl_add_u64 v[240:241], s[64:65], 0, v[190:191]
	s_mov_b32 m0, s66
	v_lshl_add_u64 v[242:243], s[56:57], 0, v[144:145]
	global_load_lds_dwordx4 v[240:241], off
	v_lshl_add_u64 v[240:241], s[64:65], 0, v[146:147]
	s_add_i32 m0, s66, 0x2000
	s_nop 0
	global_load_lds_dwordx4 v[240:241], off
	v_lshl_add_u64 v[240:241], s[56:57], 0, v[142:143]
	s_mov_b32 m0, s21
	s_nop 0
	global_load_lds_dwordx4 v[240:241], off
	s_mov_b32 m0, s23
	s_nop 0
	global_load_lds_dwordx4 v[242:243], off
	s_waitcnt vmcnt(8)
	s_waitcnt lgkmcnt(0)
	s_barrier
	s_setprio 1
	s_waitcnt lgkmcnt(0)
	v_mfma_f32_16x16x32_bf16 v[66:69], v[134:137], v[182:185], v[66:69]
	v_mfma_f32_16x16x32_bf16 v[62:65], v[152:155], v[182:185], v[62:65]
	v_mfma_f32_16x16x32_bf16 v[50:53], v[134:137], v[198:201], v[50:53]
	v_mfma_f32_16x16x32_bf16 v[46:49], v[152:155], v[198:201], v[46:49]
	v_mfma_f32_16x16x32_bf16 v[34:37], v[134:137], v[206:209], v[34:37]
	v_mfma_f32_16x16x32_bf16 v[30:33], v[152:155], v[206:209], v[30:33]
	v_mfma_f32_16x16x32_bf16 v[18:21], v[134:137], v[214:217], v[18:21]
	v_mfma_f32_16x16x32_bf16 v[14:17], v[152:155], v[214:217], v[14:17]
	v_mfma_f32_16x16x32_bf16 v[66:69], v[138:141], v[186:189], v[66:69]
	v_mfma_f32_16x16x32_bf16 v[62:65], v[156:159], v[186:189], v[62:65]
	v_mfma_f32_16x16x32_bf16 v[50:53], v[138:141], v[202:205], v[50:53]
	v_mfma_f32_16x16x32_bf16 v[46:49], v[156:159], v[202:205], v[46:49]
	v_mfma_f32_16x16x32_bf16 v[34:37], v[138:141], v[210:213], v[34:37]
	v_mfma_f32_16x16x32_bf16 v[30:33], v[156:159], v[210:213], v[30:33]
	v_mfma_f32_16x16x32_bf16 v[18:21], v[138:141], v[236:239], v[18:21]
	v_mfma_f32_16x16x32_bf16 v[14:17], v[156:159], v[236:239], v[14:17]
	s_setprio 0
	s_setprio 1
	v_mfma_f32_16x16x32_bf16 v[58:61], v[166:169], v[182:185], v[58:61]
	v_mfma_f32_16x16x32_bf16 v[54:57], v[174:177], v[182:185], v[54:57]
	v_mfma_f32_16x16x32_bf16 v[42:45], v[166:169], v[198:201], v[42:45]
	v_mfma_f32_16x16x32_bf16 v[38:41], v[174:177], v[198:201], v[38:41]
	v_mfma_f32_16x16x32_bf16 v[26:29], v[166:169], v[206:209], v[26:29]
	v_mfma_f32_16x16x32_bf16 v[22:25], v[174:177], v[206:209], v[22:25]
	v_mfma_f32_16x16x32_bf16 v[10:13], v[166:169], v[214:217], v[10:13]
	v_mfma_f32_16x16x32_bf16 v[6:9], v[174:177], v[214:217], v[6:9]
	v_mfma_f32_16x16x32_bf16 v[58:61], v[170:173], v[186:189], v[58:61]
	v_mfma_f32_16x16x32_bf16 v[54:57], v[178:181], v[186:189], v[54:57]
	v_mfma_f32_16x16x32_bf16 v[42:45], v[170:173], v[202:205], v[42:45]
	v_mfma_f32_16x16x32_bf16 v[38:41], v[178:181], v[202:205], v[38:41]
	v_mfma_f32_16x16x32_bf16 v[26:29], v[170:173], v[210:213], v[26:29]
	v_mfma_f32_16x16x32_bf16 v[22:25], v[178:181], v[210:213], v[22:25]
	v_mfma_f32_16x16x32_bf16 v[10:13], v[170:173], v[236:239], v[10:13]
	v_mfma_f32_16x16x32_bf16 v[6:9], v[178:181], v[236:239], v[6:9]
	s_setprio 0
	s_barrier
	s_add_i32 s64, 0, 0x18000
	s_add_i32 s65, 0, 0x1c000
	v_add_u32_e32 v156, s64, v163
	v_add_u32_e32 v178, s65, v163
	ds_read_b128 v[134:137], v156
	ds_read_b128 v[138:141], v156 offset:1024
	ds_read_b128 v[152:155], v156 offset:2048
	ds_read_b128 v[156:159], v156 offset:3072
	ds_read_b128 v[166:169], v178
	ds_read_b128 v[170:173], v178 offset:1024
	ds_read_b128 v[174:177], v178 offset:2048
	ds_read_b128 v[178:181], v178 offset:3072
	s_add_u32 s56, s56, 0x80000
	s_addc_u32 s57, s57, 0
	s_mov_b32 m0, s26
	v_lshl_add_u64 v[244:245], s[56:57], 0, v[142:143]
	ds_read_b128 v[182:185], v165 offset:32768
	ds_read_b128 v[186:189], v165 offset:33792
	ds_read_b128 v[198:201], v165 offset:34816
	ds_read_b128 v[202:205], v165 offset:35840
	ds_read_b128 v[206:209], v165 offset:36864
	ds_read_b128 v[210:213], v165 offset:37888
	ds_read_b128 v[214:217], v165 offset:38912
	ds_read_b128 v[236:239], v165 offset:39936
	global_load_lds_dwordx4 v[244:245], off
	v_lshl_add_u64 v[244:245], s[56:57], 0, v[144:145]
	s_mov_b32 m0, s29
	s_nop 0
	global_load_lds_dwordx4 v[244:245], off
	s_waitcnt vmcnt(8)
	s_waitcnt lgkmcnt(0)
	s_barrier
	s_setprio 1
	s_waitcnt lgkmcnt(0)
	v_mfma_f32_16x16x32_bf16 v[130:133], v[134:137], v[182:185], v[130:133]
	v_mfma_f32_16x16x32_bf16 v[126:129], v[152:155], v[182:185], v[126:129]
	v_mfma_f32_16x16x32_bf16 v[114:117], v[134:137], v[198:201], v[114:117]
	v_mfma_f32_16x16x32_bf16 v[110:113], v[152:155], v[198:201], v[110:113]
	v_mfma_f32_16x16x32_bf16 v[98:101], v[134:137], v[206:209], v[98:101]
	v_mfma_f32_16x16x32_bf16 v[94:97], v[152:155], v[206:209], v[94:97]
	v_mfma_f32_16x16x32_bf16 v[82:85], v[134:137], v[214:217], v[82:85]
	v_mfma_f32_16x16x32_bf16 v[78:81], v[152:155], v[214:217], v[78:81]
	v_mfma_f32_16x16x32_bf16 v[130:133], v[138:141], v[186:189], v[130:133]
	v_mfma_f32_16x16x32_bf16 v[126:129], v[156:159], v[186:189], v[126:129]
	v_mfma_f32_16x16x32_bf16 v[114:117], v[138:141], v[202:205], v[114:117]
	v_mfma_f32_16x16x32_bf16 v[110:113], v[156:159], v[202:205], v[110:113]
	v_mfma_f32_16x16x32_bf16 v[98:101], v[138:141], v[210:213], v[98:101]
	v_mfma_f32_16x16x32_bf16 v[94:97], v[156:159], v[210:213], v[94:97]
	v_mfma_f32_16x16x32_bf16 v[82:85], v[138:141], v[236:239], v[82:85]
	v_mfma_f32_16x16x32_bf16 v[78:81], v[156:159], v[236:239], v[78:81]
	s_setprio 0
	s_setprio 1
	v_mfma_f32_16x16x32_bf16 v[122:125], v[166:169], v[182:185], v[122:125]
	v_mfma_f32_16x16x32_bf16 v[118:121], v[174:177], v[182:185], v[118:121]
	v_mfma_f32_16x16x32_bf16 v[106:109], v[166:169], v[198:201], v[106:109]
	v_mfma_f32_16x16x32_bf16 v[102:105], v[174:177], v[198:201], v[102:105]
	v_mfma_f32_16x16x32_bf16 v[90:93], v[166:169], v[206:209], v[90:93]
	v_mfma_f32_16x16x32_bf16 v[86:89], v[174:177], v[206:209], v[86:89]
	v_mfma_f32_16x16x32_bf16 v[74:77], v[166:169], v[214:217], v[74:77]
	v_mfma_f32_16x16x32_bf16 v[70:73], v[174:177], v[214:217], v[70:73]
	v_mfma_f32_16x16x32_bf16 v[122:125], v[170:173], v[186:189], v[122:125]
	v_mfma_f32_16x16x32_bf16 v[118:121], v[178:181], v[186:189], v[118:121]
	v_mfma_f32_16x16x32_bf16 v[106:109], v[170:173], v[202:205], v[106:109]
	v_mfma_f32_16x16x32_bf16 v[102:105], v[178:181], v[202:205], v[102:105]
	v_mfma_f32_16x16x32_bf16 v[90:93], v[170:173], v[210:213], v[90:93]
	v_mfma_f32_16x16x32_bf16 v[86:89], v[178:181], v[210:213], v[86:89]
	v_mfma_f32_16x16x32_bf16 v[74:77], v[170:173], v[236:239], v[74:77]
	v_mfma_f32_16x16x32_bf16 v[70:73], v[178:181], v[236:239], v[70:73]
	s_setprio 0
	s_barrier
	s_add_i32 s56, s64, s15
	v_lshl_add_u64 v[160:161], v[160:161], 0, s[30:31]
	s_mov_b32 m0, s56
	ds_read_b128 v[182:185], v165 offset:49152
	ds_read_b128 v[186:189], v165 offset:50176
	ds_read_b128 v[198:201], v165 offset:51200
	ds_read_b128 v[202:205], v165 offset:52224
	ds_read_b128 v[206:209], v165 offset:53248
	ds_read_b128 v[210:213], v165 offset:54272
	ds_read_b128 v[214:217], v165 offset:55296
	ds_read_b128 v[236:239], v165 offset:56320
	global_load_lds_dwordx4 v[160:161], off
	s_add_i32 m0, s56, 0x2000
	s_add_u32 s54, s54, 0x80080
	v_lshl_add_u64 v[160:161], v[218:219], 0, s[30:31]
	s_addc_u32 s55, s55, 0
	s_add_i32 s56, s65, s15
	global_load_lds_dwordx4 v[160:161], off
	v_lshl_add_u64 v[160:161], s[54:55], 0, v[190:191]
	s_mov_b32 m0, s56
	s_nop 0
	global_load_lds_dwordx4 v[160:161], off
	v_lshl_add_u64 v[160:161], s[54:55], 0, v[146:147]
	s_add_i32 m0, s56, 0x2000
	s_nop 0
	global_load_lds_dwordx4 v[160:161], off
	v_lshl_add_u64 v[160:161], v[240:241], 0, s[30:31]
	s_mov_b32 m0, s51
	s_nop 0
	global_load_lds_dwordx4 v[160:161], off
	v_lshl_add_u64 v[160:161], v[242:243], 0, s[30:31]
	s_mov_b32 m0, s58
	s_nop 0
	global_load_lds_dwordx4 v[160:161], off
	s_waitcnt vmcnt(8)
	s_waitcnt lgkmcnt(0)
	s_barrier
	s_setprio 1
	s_waitcnt lgkmcnt(0)
	v_mfma_f32_16x16x32_bf16 v[66:69], v[134:137], v[182:185], v[66:69]
	v_mfma_f32_16x16x32_bf16 v[62:65], v[152:155], v[182:185], v[62:65]
	v_mfma_f32_16x16x32_bf16 v[50:53], v[134:137], v[198:201], v[50:53]
	v_mfma_f32_16x16x32_bf16 v[46:49], v[152:155], v[198:201], v[46:49]
	v_mfma_f32_16x16x32_bf16 v[34:37], v[134:137], v[206:209], v[34:37]
	v_mfma_f32_16x16x32_bf16 v[30:33], v[152:155], v[206:209], v[30:33]
	v_mfma_f32_16x16x32_bf16 v[18:21], v[134:137], v[214:217], v[18:21]
	v_mfma_f32_16x16x32_bf16 v[14:17], v[152:155], v[214:217], v[14:17]
	v_mfma_f32_16x16x32_bf16 v[66:69], v[138:141], v[186:189], v[66:69]
	v_mfma_f32_16x16x32_bf16 v[62:65], v[156:159], v[186:189], v[62:65]
	v_mfma_f32_16x16x32_bf16 v[50:53], v[138:141], v[202:205], v[50:53]
	v_mfma_f32_16x16x32_bf16 v[46:49], v[156:159], v[202:205], v[46:49]
	v_mfma_f32_16x16x32_bf16 v[34:37], v[138:141], v[210:213], v[34:37]
	v_mfma_f32_16x16x32_bf16 v[30:33], v[156:159], v[210:213], v[30:33]
	v_mfma_f32_16x16x32_bf16 v[18:21], v[138:141], v[236:239], v[18:21]
	v_mfma_f32_16x16x32_bf16 v[14:17], v[156:159], v[236:239], v[14:17]
	s_setprio 0
	s_setprio 1
	v_mfma_f32_16x16x32_bf16 v[58:61], v[166:169], v[182:185], v[58:61]
	v_mfma_f32_16x16x32_bf16 v[54:57], v[174:177], v[182:185], v[54:57]
	v_mfma_f32_16x16x32_bf16 v[42:45], v[166:169], v[198:201], v[42:45]
	v_mfma_f32_16x16x32_bf16 v[38:41], v[174:177], v[198:201], v[38:41]
	v_mfma_f32_16x16x32_bf16 v[26:29], v[166:169], v[206:209], v[26:29]
	v_mfma_f32_16x16x32_bf16 v[22:25], v[174:177], v[206:209], v[22:25]
	v_mfma_f32_16x16x32_bf16 v[10:13], v[166:169], v[214:217], v[10:13]
	v_mfma_f32_16x16x32_bf16 v[6:9], v[174:177], v[214:217], v[6:9]
	v_mfma_f32_16x16x32_bf16 v[58:61], v[170:173], v[186:189], v[58:61]
	v_mfma_f32_16x16x32_bf16 v[54:57], v[178:181], v[186:189], v[54:57]
	v_mfma_f32_16x16x32_bf16 v[42:45], v[170:173], v[202:205], v[42:45]
	v_mfma_f32_16x16x32_bf16 v[38:41], v[178:181], v[202:205], v[38:41]
	v_mfma_f32_16x16x32_bf16 v[26:29], v[170:173], v[210:213], v[26:29]
	v_mfma_f32_16x16x32_bf16 v[22:25], v[178:181], v[210:213], v[22:25]
	v_mfma_f32_16x16x32_bf16 v[10:13], v[170:173], v[236:239], v[10:13]
	v_mfma_f32_16x16x32_bf16 v[6:9], v[178:181], v[236:239], v[6:9]
	s_setprio 0
	s_barrier
	s_add_i32 s63, s63, 2
	s_add_u32 s61, s61, 0x100
	s_addc_u32 s62, s62, 0
	s_add_u32 s52, s52, 0x100
	s_addc_u32 s53, s53, 0
	s_cmp_gt_u32 s63, 29
	s_cbranch_scc0 .LBB0_110
	v_lshl_add_u32 v246, s80, 9, v235
	v_lshlrev_b32_e32 v246, 7, v246
	v_add_u32_e32 v248, 0x3400000, v246
	v_add_u32_e32 v246, 0x2400000, v246
	v_mov_b32_e32 v247, 0
	v_mov_b32_e32 v249, 0
	v_lshl_add_u64 v[246:247], s[12:13], 0, v[246:247]
	v_lshl_add_u64 v[248:249], s[12:13], 0, v[248:249]
	global_load_dword v250, v[246:247], off
	global_load_dword v250, v[248:249], off
	v_lshl_or_b32 v152, s50, 8, v164
	v_lshl_add_u32 v154, s48, 8, v162
	v_ashrrev_i32_e32 v153, 31, v152
	v_readlane_b32 s4, v255, 14
	v_ashrrev_i32_e32 v155, 31, v154
	v_lshlrev_b64 v[176:177], 1, v[152:153]
	v_readlane_b32 s5, v255, 15
	v_lshlrev_b64 v[158:159], 12, v[154:155]
	v_or_b32_e32 v160, 16, v154
	v_lshl_add_u64 v[156:157], s[4:5], 0, v[176:177]
	v_lshl_add_u64 v[134:135], v[156:157], 0, v[158:159]
	global_load_dwordx4 v[168:171], v[134:135], off
	global_load_dwordx4 v[172:175], v[134:135], off offset:256
	v_ashrrev_i32_e32 v161, 31, v160
	v_lshlrev_b64 v[134:135], 12, v[160:161]
	v_lshl_add_u64 v[134:135], v[156:157], 0, v[134:135]
	global_load_dwordx4 v[138:141], v[134:135], off
	s_nop 0
	global_load_dwordx4 v[134:137], v[134:135], off offset:256
	v_and_b32_e32 v167, 64, v221
	v_xor_b32_e32 v166, 16, v221
	v_add_u32_e32 v167, 64, v167
	v_xor_b32_e32 v178, 32, v221
	v_cmp_lt_i32_e32 vcc, v166, v167
	s_waitcnt vmcnt(0)
	v_lshlrev_b32_e32 v180, 16, v170
	v_cndmask_b32_e32 v166, v221, v166, vcc
	v_cmp_lt_i32_e32 vcc, v178, v167
	v_and_b32_e32 v181, 0xffff0000, v170
	v_lshlrev_b32_e32 v170, 16, v171
	v_cndmask_b32_e32 v167, v221, v178, vcc
	v_lshl_add_u64 v[178:179], s[4:5], 0, v[158:159]
	v_lshl_add_u64 v[176:177], v[178:179], 0, v[176:177]
	v_lshlrev_b32_e32 v178, 16, v168
	v_and_b32_e32 v179, 0xffff0000, v168
	v_lshlrev_b32_e32 v168, 16, v169
	v_and_b32_e32 v169, 0xffff0000, v169
	v_and_b32_e32 v171, 0xffff0000, v171
	v_lshlrev_b32_e32 v182, 16, v172
	v_and_b32_e32 v183, 0xffff0000, v172
	v_lshlrev_b32_e32 v172, 16, v173
	v_and_b32_e32 v173, 0xffff0000, v173
	v_lshlrev_b32_e32 v184, 16, v174
	v_and_b32_e32 v185, 0xffff0000, v174
	v_lshlrev_b32_e32 v174, 16, v175
	v_and_b32_e32 v175, 0xffff0000, v175
	v_pk_add_f32 v[132:133], v[132:133], v[168:169]
	v_pk_add_f32 v[130:131], v[130:131], v[178:179]
	v_pk_add_f32 v[128:129], v[128:129], v[170:171]
	v_pk_add_f32 v[126:127], v[126:127], v[180:181]
	v_pk_add_f32 v[168:169], v[124:125], v[172:173]
	v_pk_add_f32 v[122:123], v[122:123], v[182:183]
	v_pk_add_f32 v[170:171], v[120:121], v[174:175]
	v_pk_add_f32 v[172:173], v[118:119], v[184:185]
	v_mul_f32_e32 v121, v131, v131
	v_mul_f32_e32 v124, v133, v133
	v_mul_f32_e32 v125, v127, v127
	v_mul_f32_e32 v174, v129, v129
	v_cvt_pk_bf16_f32 v118, v130, v131
	v_cvt_pk_bf16_f32 v119, v132, v133
	v_cvt_pk_bf16_f32 v120, v126, v127
	v_mul_f32_e32 v127, v123, v123
	v_mul_f32_e32 v131, v169, v169
	v_mul_f32_e32 v133, v173, v173
	v_mul_f32_e32 v175, v171, v171
	v_fmac_f32_e32 v121, v130, v130
	v_fmac_f32_e32 v124, v132, v132
	v_fmac_f32_e32 v125, v126, v126
	v_fmac_f32_e32 v174, v128, v128
	v_fmac_f32_e32 v127, v122, v122
	v_fmac_f32_e32 v131, v168, v168
	v_fmac_f32_e32 v133, v172, v172
	v_fmac_f32_e32 v175, v170, v170
	v_add_f32_e32 v121, v121, v124
	v_add_f32_e32 v124, v125, v174
	v_add_f32_e32 v125, v127, v131
	v_add_f32_e32 v126, v133, v175
	v_add_f32_e32 v121, v121, v124
	v_add_f32_e32 v124, v125, v126
	v_lshlrev_b32_e32 v166, 2, v166
	v_add_f32_e32 v126, v121, v124
	ds_bpermute_b32 v127, v166, v126
	v_cvt_pk_bf16_f32 v121, v128, v129
	global_store_dwordx4 v[176:177], v[118:121], off
	v_cvt_pk_bf16_f32 v124, v122, v123
	v_cvt_pk_bf16_f32 v125, v168, v169
	s_waitcnt lgkmcnt(0)
	s_nop 0
	v_add_f32_e32 v121, v126, v127
	v_lshlrev_b32_e32 v120, 2, v167
	ds_bpermute_b32 v122, v120, v121
	v_lshl_add_u64 v[118:119], v[154:155], 3, s[18:19]
	v_cvt_pk_bf16_f32 v126, v172, v173
	v_cvt_pk_bf16_f32 v127, v170, v171
	global_store_dwordx4 v[176:177], v[124:127], off offset:256
	s_and_saveexec_b64 s[4:5], s[38:39]
	s_cbranch_execz .LBB0_113
	s_waitcnt lgkmcnt(0)
	v_add_f32_e32 v121, v121, v122
	v_mul_f32_e32 v121, 0x4b800000, v121
	v_trunc_f32_e32 v121, v121
	v_mul_f32_e32 v122, 0x2f800000, v121
	v_floor_f32_e32 v123, v122
	v_fmac_f32_e32 v121, 0xcf800000, v123
	v_cvt_u32_f32_e32 v122, v121
	v_cvt_u32_f32_e32 v123, v123
	global_atomic_add_x2 v[118:119], v[122:123], off

.LBB0_150:
	s_add_u32 s54, s52, 0xfff80080
	s_addc_u32 s55, s53, -1
	s_add_i32 s64, 0, 0x10000
	s_cmp_eq_u32 s63, 28
	s_cselect_b32 s57, s4, s55
	s_cselect_b32 s56, s5, s54
	s_cselect_b32 s55, s37, s62
	s_cselect_b32 s54, s43, s61
	s_add_i32 s66, 0, 0x14000
	v_add_u32_e32 v146, s64, v169
	v_add_u32_e32 v176, s66, v169
	ds_read_b128 v[134:137], v146
	ds_read_b128 v[138:141], v146 offset:1024
	ds_read_b128 v[142:145], v146 offset:2048
	ds_read_b128 v[146:149], v146 offset:3072
	ds_read_b128 v[160:163], v176
	ds_read_b128 v[164:167], v176 offset:1024
	ds_read_b128 v[172:175], v176 offset:2048
	ds_read_b128 v[176:179], v176 offset:3072
	v_lshl_add_u64 v[188:189], s[52:53], 0, v[158:159]
	s_add_i32 m0, s21, 0xc000
	ds_read_b128 v[180:183], v171
	ds_read_b128 v[184:187], v171 offset:1024
	ds_read_b128 v[198:201], v171 offset:2048
	ds_read_b128 v[202:205], v171 offset:3072
	ds_read_b128 v[206:209], v171 offset:4096
	ds_read_b128 v[210:213], v171 offset:5120
	ds_read_b128 v[214:217], v171 offset:6144
	ds_read_b128 v[236:239], v171 offset:7168
	global_load_lds_dwordx4 v[188:189], off
	v_lshl_add_u64 v[188:189], s[52:53], 0, v[156:157]
	s_add_i32 m0, s21, 0xe000
	s_nop 0
	global_load_lds_dwordx4 v[188:189], off
	s_waitcnt vmcnt(8)
	s_waitcnt lgkmcnt(0)
	s_barrier
	s_setprio 1
	s_waitcnt lgkmcnt(0)
	v_mfma_f32_16x16x32_bf16 v[130:133], v[134:137], v[180:183], v[130:133]
	v_mfma_f32_16x16x32_bf16 v[126:129], v[142:145], v[180:183], v[126:129]
	v_mfma_f32_16x16x32_bf16 v[114:117], v[134:137], v[198:201], v[114:117]
	v_mfma_f32_16x16x32_bf16 v[110:113], v[142:145], v[198:201], v[110:113]
	v_mfma_f32_16x16x32_bf16 v[98:101], v[134:137], v[206:209], v[98:101]
	v_mfma_f32_16x16x32_bf16 v[94:97], v[142:145], v[206:209], v[94:97]
	v_mfma_f32_16x16x32_bf16 v[82:85], v[134:137], v[214:217], v[82:85]
	v_mfma_f32_16x16x32_bf16 v[78:81], v[142:145], v[214:217], v[78:81]
	v_mfma_f32_16x16x32_bf16 v[130:133], v[138:141], v[184:187], v[130:133]
	v_mfma_f32_16x16x32_bf16 v[126:129], v[146:149], v[184:187], v[126:129]
	v_mfma_f32_16x16x32_bf16 v[114:117], v[138:141], v[202:205], v[114:117]
	v_mfma_f32_16x16x32_bf16 v[110:113], v[146:149], v[202:205], v[110:113]
	v_mfma_f32_16x16x32_bf16 v[98:101], v[138:141], v[210:213], v[98:101]
	v_mfma_f32_16x16x32_bf16 v[94:97], v[146:149], v[210:213], v[94:97]
	v_mfma_f32_16x16x32_bf16 v[82:85], v[138:141], v[236:239], v[82:85]
	v_mfma_f32_16x16x32_bf16 v[78:81], v[146:149], v[236:239], v[78:81]
	s_setprio 0
	s_setprio 1
	v_mfma_f32_16x16x32_bf16 v[122:125], v[160:163], v[180:183], v[122:125]
	v_mfma_f32_16x16x32_bf16 v[118:121], v[172:175], v[180:183], v[118:121]
	v_mfma_f32_16x16x32_bf16 v[106:109], v[160:163], v[198:201], v[106:109]
	v_mfma_f32_16x16x32_bf16 v[102:105], v[172:175], v[198:201], v[102:105]
	v_mfma_f32_16x16x32_bf16 v[90:93], v[160:163], v[206:209], v[90:93]
	v_mfma_f32_16x16x32_bf16 v[86:89], v[172:175], v[206:209], v[86:89]
	v_mfma_f32_16x16x32_bf16 v[74:77], v[160:163], v[214:217], v[74:77]
	v_mfma_f32_16x16x32_bf16 v[70:73], v[172:175], v[214:217], v[70:73]
	v_mfma_f32_16x16x32_bf16 v[122:125], v[164:167], v[184:187], v[122:125]
	v_mfma_f32_16x16x32_bf16 v[118:121], v[176:179], v[184:187], v[118:121]
	v_mfma_f32_16x16x32_bf16 v[106:109], v[164:167], v[202:205], v[106:109]
	v_mfma_f32_16x16x32_bf16 v[102:105], v[176:179], v[202:205], v[102:105]
	v_mfma_f32_16x16x32_bf16 v[90:93], v[164:167], v[210:213], v[90:93]
	v_mfma_f32_16x16x32_bf16 v[86:89], v[176:179], v[210:213], v[86:89]
	v_mfma_f32_16x16x32_bf16 v[74:77], v[164:167], v[236:239], v[74:77]
	v_mfma_f32_16x16x32_bf16 v[70:73], v[176:179], v[236:239], v[70:73]
	s_setprio 0
	s_barrier
	s_add_i32 s64, s64, s15
	v_lshl_add_u64 v[188:189], s[54:55], 0, v[190:191]
	s_mov_b32 m0, s64
	ds_read_b128 v[180:183], v171 offset:16384
	ds_read_b128 v[184:187], v171 offset:17408
	ds_read_b128 v[198:201], v171 offset:18432
	ds_read_b128 v[202:205], v171 offset:19456
	ds_read_b128 v[206:209], v171 offset:20480
	ds_read_b128 v[210:213], v171 offset:21504
	ds_read_b128 v[214:217], v171 offset:22528
	ds_read_b128 v[236:239], v171 offset:23552
	global_load_lds_dwordx4 v[188:189], off
	s_add_i32 m0, s64, 0x2000
	s_add_u32 s64, s54, 0x80000
	v_lshl_add_u64 v[218:219], s[54:55], 0, v[154:155]
	s_addc_u32 s65, s55, 0
	s_add_i32 s66, s66, s15
	global_load_lds_dwordx4 v[218:219], off
	v_lshl_add_u64 v[240:241], s[64:65], 0, v[190:191]
	s_mov_b32 m0, s66
	v_lshl_add_u64 v[242:243], s[56:57], 0, v[152:153]
	global_load_lds_dwordx4 v[240:241], off
	v_lshl_add_u64 v[240:241], s[64:65], 0, v[154:155]
	s_add_i32 m0, s66, 0x2000
	s_nop 0
	global_load_lds_dwordx4 v[240:241], off
	v_lshl_add_u64 v[240:241], s[56:57], 0, v[150:151]
	s_mov_b32 m0, s21
	s_nop 0
	global_load_lds_dwordx4 v[240:241], off
	s_mov_b32 m0, s23
	s_nop 0
	global_load_lds_dwordx4 v[242:243], off
	s_waitcnt vmcnt(8)
	s_waitcnt lgkmcnt(0)
	s_barrier
	s_setprio 1
	s_waitcnt lgkmcnt(0)
	v_mfma_f32_16x16x32_bf16 v[66:69], v[134:137], v[180:183], v[66:69]
	v_mfma_f32_16x16x32_bf16 v[62:65], v[142:145], v[180:183], v[62:65]
	v_mfma_f32_16x16x32_bf16 v[50:53], v[134:137], v[198:201], v[50:53]
	v_mfma_f32_16x16x32_bf16 v[46:49], v[142:145], v[198:201], v[46:49]
	v_mfma_f32_16x16x32_bf16 v[34:37], v[134:137], v[206:209], v[34:37]
	v_mfma_f32_16x16x32_bf16 v[30:33], v[142:145], v[206:209], v[30:33]
	v_mfma_f32_16x16x32_bf16 v[18:21], v[134:137], v[214:217], v[18:21]
	v_mfma_f32_16x16x32_bf16 v[14:17], v[142:145], v[214:217], v[14:17]
	v_mfma_f32_16x16x32_bf16 v[66:69], v[138:141], v[184:187], v[66:69]
	v_mfma_f32_16x16x32_bf16 v[62:65], v[146:149], v[184:187], v[62:65]
	v_mfma_f32_16x16x32_bf16 v[50:53], v[138:141], v[202:205], v[50:53]
	v_mfma_f32_16x16x32_bf16 v[46:49], v[146:149], v[202:205], v[46:49]
	v_mfma_f32_16x16x32_bf16 v[34:37], v[138:141], v[210:213], v[34:37]
	v_mfma_f32_16x16x32_bf16 v[30:33], v[146:149], v[210:213], v[30:33]
	v_mfma_f32_16x16x32_bf16 v[18:21], v[138:141], v[236:239], v[18:21]
	v_mfma_f32_16x16x32_bf16 v[14:17], v[146:149], v[236:239], v[14:17]
	s_setprio 0
	s_setprio 1
	v_mfma_f32_16x16x32_bf16 v[58:61], v[160:163], v[180:183], v[58:61]
	v_mfma_f32_16x16x32_bf16 v[54:57], v[172:175], v[180:183], v[54:57]
	v_mfma_f32_16x16x32_bf16 v[42:45], v[160:163], v[198:201], v[42:45]
	v_mfma_f32_16x16x32_bf16 v[38:41], v[172:175], v[198:201], v[38:41]
	v_mfma_f32_16x16x32_bf16 v[26:29], v[160:163], v[206:209], v[26:29]
	v_mfma_f32_16x16x32_bf16 v[22:25], v[172:175], v[206:209], v[22:25]
	v_mfma_f32_16x16x32_bf16 v[10:13], v[160:163], v[214:217], v[10:13]
	v_mfma_f32_16x16x32_bf16 v[6:9], v[172:175], v[214:217], v[6:9]
	v_mfma_f32_16x16x32_bf16 v[58:61], v[164:167], v[184:187], v[58:61]
	v_mfma_f32_16x16x32_bf16 v[54:57], v[176:179], v[184:187], v[54:57]
	v_mfma_f32_16x16x32_bf16 v[42:45], v[164:167], v[202:205], v[42:45]
	v_mfma_f32_16x16x32_bf16 v[38:41], v[176:179], v[202:205], v[38:41]
	v_mfma_f32_16x16x32_bf16 v[26:29], v[164:167], v[210:213], v[26:29]
	v_mfma_f32_16x16x32_bf16 v[22:25], v[176:179], v[210:213], v[22:25]
	v_mfma_f32_16x16x32_bf16 v[10:13], v[164:167], v[236:239], v[10:13]
	v_mfma_f32_16x16x32_bf16 v[6:9], v[176:179], v[236:239], v[6:9]
	s_setprio 0
	s_barrier
	s_add_i32 s64, 0, 0x18000
	s_add_i32 s65, 0, 0x1c000
	v_add_u32_e32 v146, s64, v169
	v_add_u32_e32 v176, s65, v169
	ds_read_b128 v[134:137], v146
	ds_read_b128 v[138:141], v146 offset:1024
	ds_read_b128 v[142:145], v146 offset:2048
	ds_read_b128 v[146:149], v146 offset:3072
	ds_read_b128 v[160:163], v176
	ds_read_b128 v[164:167], v176 offset:1024
	ds_read_b128 v[172:175], v176 offset:2048
	ds_read_b128 v[176:179], v176 offset:3072
	s_add_u32 s56, s56, 0x80000
	s_addc_u32 s57, s57, 0
	s_mov_b32 m0, s26
	v_lshl_add_u64 v[244:245], s[56:57], 0, v[150:151]
	ds_read_b128 v[180:183], v171 offset:32768
	ds_read_b128 v[184:187], v171 offset:33792
	ds_read_b128 v[198:201], v171 offset:34816
	ds_read_b128 v[202:205], v171 offset:35840
	ds_read_b128 v[206:209], v171 offset:36864
	ds_read_b128 v[210:213], v171 offset:37888
	ds_read_b128 v[214:217], v171 offset:38912
	ds_read_b128 v[236:239], v171 offset:39936
	global_load_lds_dwordx4 v[244:245], off
	v_lshl_add_u64 v[244:245], s[56:57], 0, v[152:153]
	s_mov_b32 m0, s29
	s_nop 0
	global_load_lds_dwordx4 v[244:245], off
	s_waitcnt vmcnt(8)
	s_waitcnt lgkmcnt(0)
	s_barrier
	s_setprio 1
	s_waitcnt lgkmcnt(0)
	v_mfma_f32_16x16x32_bf16 v[130:133], v[134:137], v[180:183], v[130:133]
	v_mfma_f32_16x16x32_bf16 v[126:129], v[142:145], v[180:183], v[126:129]
	v_mfma_f32_16x16x32_bf16 v[114:117], v[134:137], v[198:201], v[114:117]
	v_mfma_f32_16x16x32_bf16 v[110:113], v[142:145], v[198:201], v[110:113]
	v_mfma_f32_16x16x32_bf16 v[98:101], v[134:137], v[206:209], v[98:101]
	v_mfma_f32_16x16x32_bf16 v[94:97], v[142:145], v[206:209], v[94:97]
	v_mfma_f32_16x16x32_bf16 v[82:85], v[134:137], v[214:217], v[82:85]
	v_mfma_f32_16x16x32_bf16 v[78:81], v[142:145], v[214:217], v[78:81]
	v_mfma_f32_16x16x32_bf16 v[130:133], v[138:141], v[184:187], v[130:133]
	v_mfma_f32_16x16x32_bf16 v[126:129], v[146:149], v[184:187], v[126:129]
	v_mfma_f32_16x16x32_bf16 v[114:117], v[138:141], v[202:205], v[114:117]
	v_mfma_f32_16x16x32_bf16 v[110:113], v[146:149], v[202:205], v[110:113]
	v_mfma_f32_16x16x32_bf16 v[98:101], v[138:141], v[210:213], v[98:101]
	v_mfma_f32_16x16x32_bf16 v[94:97], v[146:149], v[210:213], v[94:97]
	v_mfma_f32_16x16x32_bf16 v[82:85], v[138:141], v[236:239], v[82:85]
	v_mfma_f32_16x16x32_bf16 v[78:81], v[146:149], v[236:239], v[78:81]
	s_setprio 0
	s_setprio 1
	v_mfma_f32_16x16x32_bf16 v[122:125], v[160:163], v[180:183], v[122:125]
	v_mfma_f32_16x16x32_bf16 v[118:121], v[172:175], v[180:183], v[118:121]
	v_mfma_f32_16x16x32_bf16 v[106:109], v[160:163], v[198:201], v[106:109]
	v_mfma_f32_16x16x32_bf16 v[102:105], v[172:175], v[198:201], v[102:105]
	v_mfma_f32_16x16x32_bf16 v[90:93], v[160:163], v[206:209], v[90:93]
	v_mfma_f32_16x16x32_bf16 v[86:89], v[172:175], v[206:209], v[86:89]
	v_mfma_f32_16x16x32_bf16 v[74:77], v[160:163], v[214:217], v[74:77]
	v_mfma_f32_16x16x32_bf16 v[70:73], v[172:175], v[214:217], v[70:73]
	v_mfma_f32_16x16x32_bf16 v[122:125], v[164:167], v[184:187], v[122:125]
	v_mfma_f32_16x16x32_bf16 v[118:121], v[176:179], v[184:187], v[118:121]
	v_mfma_f32_16x16x32_bf16 v[106:109], v[164:167], v[202:205], v[106:109]
	v_mfma_f32_16x16x32_bf16 v[102:105], v[176:179], v[202:205], v[102:105]
	v_mfma_f32_16x16x32_bf16 v[90:93], v[164:167], v[210:213], v[90:93]
	v_mfma_f32_16x16x32_bf16 v[86:89], v[176:179], v[210:213], v[86:89]
	v_mfma_f32_16x16x32_bf16 v[74:77], v[164:167], v[236:239], v[74:77]
	v_mfma_f32_16x16x32_bf16 v[70:73], v[176:179], v[236:239], v[70:73]
	s_setprio 0
	s_barrier
	s_add_i32 s56, s64, s15
	v_lshl_add_u64 v[188:189], v[188:189], 0, s[30:31]
	s_mov_b32 m0, s56
	ds_read_b128 v[180:183], v171 offset:49152
	ds_read_b128 v[184:187], v171 offset:50176
	ds_read_b128 v[198:201], v171 offset:51200
	ds_read_b128 v[202:205], v171 offset:52224
	ds_read_b128 v[206:209], v171 offset:53248
	ds_read_b128 v[210:213], v171 offset:54272
	ds_read_b128 v[214:217], v171 offset:55296
	ds_read_b128 v[236:239], v171 offset:56320
	global_load_lds_dwordx4 v[188:189], off
	s_add_i32 m0, s56, 0x2000
	s_add_u32 s54, s54, 0x80080
	v_lshl_add_u64 v[188:189], v[218:219], 0, s[30:31]
	s_addc_u32 s55, s55, 0
	s_add_i32 s56, s65, s15
	global_load_lds_dwordx4 v[188:189], off
	v_lshl_add_u64 v[188:189], s[54:55], 0, v[190:191]
	s_mov_b32 m0, s56
	s_nop 0
	global_load_lds_dwordx4 v[188:189], off
	v_lshl_add_u64 v[188:189], s[54:55], 0, v[154:155]
	s_add_i32 m0, s56, 0x2000
	s_nop 0
	global_load_lds_dwordx4 v[188:189], off
	v_lshl_add_u64 v[188:189], v[240:241], 0, s[30:31]
	s_mov_b32 m0, s49
	s_nop 0
	global_load_lds_dwordx4 v[188:189], off
	v_lshl_add_u64 v[188:189], v[242:243], 0, s[30:31]
	s_mov_b32 m0, s51
	s_nop 0
	global_load_lds_dwordx4 v[188:189], off
	s_waitcnt vmcnt(8)
	s_waitcnt lgkmcnt(0)
	s_barrier
	s_setprio 1
	s_waitcnt lgkmcnt(0)
	v_mfma_f32_16x16x32_bf16 v[66:69], v[134:137], v[180:183], v[66:69]
	v_mfma_f32_16x16x32_bf16 v[62:65], v[142:145], v[180:183], v[62:65]
	v_mfma_f32_16x16x32_bf16 v[50:53], v[134:137], v[198:201], v[50:53]
	v_mfma_f32_16x16x32_bf16 v[46:49], v[142:145], v[198:201], v[46:49]
	v_mfma_f32_16x16x32_bf16 v[34:37], v[134:137], v[206:209], v[34:37]
	v_mfma_f32_16x16x32_bf16 v[30:33], v[142:145], v[206:209], v[30:33]
	v_mfma_f32_16x16x32_bf16 v[18:21], v[134:137], v[214:217], v[18:21]
	v_mfma_f32_16x16x32_bf16 v[14:17], v[142:145], v[214:217], v[14:17]
	v_mfma_f32_16x16x32_bf16 v[66:69], v[138:141], v[184:187], v[66:69]
	v_mfma_f32_16x16x32_bf16 v[62:65], v[146:149], v[184:187], v[62:65]
	v_mfma_f32_16x16x32_bf16 v[50:53], v[138:141], v[202:205], v[50:53]
	v_mfma_f32_16x16x32_bf16 v[46:49], v[146:149], v[202:205], v[46:49]
	v_mfma_f32_16x16x32_bf16 v[34:37], v[138:141], v[210:213], v[34:37]
	v_mfma_f32_16x16x32_bf16 v[30:33], v[146:149], v[210:213], v[30:33]
	v_mfma_f32_16x16x32_bf16 v[18:21], v[138:141], v[236:239], v[18:21]
	v_mfma_f32_16x16x32_bf16 v[14:17], v[146:149], v[236:239], v[14:17]
	s_setprio 0
	s_setprio 1
	v_mfma_f32_16x16x32_bf16 v[58:61], v[160:163], v[180:183], v[58:61]
	v_mfma_f32_16x16x32_bf16 v[54:57], v[172:175], v[180:183], v[54:57]
	v_mfma_f32_16x16x32_bf16 v[42:45], v[160:163], v[198:201], v[42:45]
	v_mfma_f32_16x16x32_bf16 v[38:41], v[172:175], v[198:201], v[38:41]
	v_mfma_f32_16x16x32_bf16 v[26:29], v[160:163], v[206:209], v[26:29]
	v_mfma_f32_16x16x32_bf16 v[22:25], v[172:175], v[206:209], v[22:25]
	v_mfma_f32_16x16x32_bf16 v[10:13], v[160:163], v[214:217], v[10:13]
	v_mfma_f32_16x16x32_bf16 v[6:9], v[172:175], v[214:217], v[6:9]
	v_mfma_f32_16x16x32_bf16 v[58:61], v[164:167], v[184:187], v[58:61]
	v_mfma_f32_16x16x32_bf16 v[54:57], v[176:179], v[184:187], v[54:57]
	v_mfma_f32_16x16x32_bf16 v[42:45], v[164:167], v[202:205], v[42:45]
	v_mfma_f32_16x16x32_bf16 v[38:41], v[176:179], v[202:205], v[38:41]
	v_mfma_f32_16x16x32_bf16 v[26:29], v[164:167], v[210:213], v[26:29]
	v_mfma_f32_16x16x32_bf16 v[22:25], v[176:179], v[210:213], v[22:25]
	v_mfma_f32_16x16x32_bf16 v[10:13], v[164:167], v[236:239], v[10:13]
	v_mfma_f32_16x16x32_bf16 v[6:9], v[176:179], v[236:239], v[6:9]
	s_setprio 0
	s_barrier
	s_add_i32 s63, s63, 2
	s_add_u32 s61, s61, 0x100
	s_addc_u32 s62, s62, 0
	s_add_u32 s52, s52, 0x100
	s_addc_u32 s53, s53, 0
	s_cmp_gt_u32 s63, 29
	s_cbranch_scc0 .LBB0_150
	v_lshl_add_u32 v246, s80, 9, v235
	v_lshlrev_b32_e32 v246, 7, v246
	v_add_u32_e32 v248, 0x3400000, v246
	v_add_u32_e32 v246, 0x2400000, v246
	v_mov_b32_e32 v247, 0
	v_mov_b32_e32 v249, 0
	v_lshl_add_u64 v[246:247], s[12:13], 0, v[246:247]
	v_lshl_add_u64 v[248:249], s[12:13], 0, v[248:249]
	global_load_dword v250, v[246:247], off
	global_load_dword v250, v[248:249], off
	s_load_dwordx2 s[4:5], s[70:71], 0x0
	v_lshl_add_u32 v162, s48, 8, v168
	v_lshl_or_b32 v160, s50, 8, v170
	v_ashrrev_i32_e32 v161, 31, v160
	v_ashrrev_i32_e32 v163, 31, v162
	s_waitcnt lgkmcnt(0)
	v_lshl_add_u64 v[164:165], v[160:161], 2, s[4:5]
	v_lshlrev_b64 v[134:135], 13, v[162:163]
	v_lshl_add_u64 v[134:135], v[164:165], 0, v[134:135]
	global_load_dwordx4 v[172:175], v[134:135], off offset:16 nt
	global_load_dwordx4 v[176:179], v[134:135], off nt
	global_load_dwordx4 v[180:183], v[134:135], off offset:528 nt
	global_load_dwordx4 v[184:187], v[134:135], off offset:512 nt
	v_or_b32_e32 v166, 16, v162
	v_ashrrev_i32_e32 v167, 31, v166
	v_lshlrev_b64 v[134:135], 13, v[166:167]
	v_lshl_add_u64 v[138:139], v[164:165], 0, v[134:135]
	global_load_dwordx4 v[142:145], v[138:139], off offset:16 nt
	global_load_dwordx4 v[146:149], v[138:139], off nt
	global_load_dwordx4 v[134:137], v[138:139], off offset:528 nt
	s_nop 0
	global_load_dwordx4 v[138:141], v[138:139], off offset:512 nt
	v_readlane_b32 s4, v255, 14
	v_lshlrev_b64 v[188:189], 12, v[162:163]
	v_readlane_b32 s5, v255, 15
	s_waitcnt vmcnt(0)
	v_pk_add_f32 v[174:175], v[128:129], v[174:175]
	v_pk_add_f32 v[132:133], v[132:133], v[178:179]
	v_pk_add_f32 v[130:131], v[130:131], v[176:177]
	v_pk_add_f32 v[128:129], v[126:127], v[172:173]
	v_mul_f32_e32 v126, v131, v131
	v_mul_f32_e32 v127, v133, v133
	v_fmac_f32_e32 v126, v130, v130
	v_fmac_f32_e32 v127, v132, v132
	v_add_f32_e32 v126, v126, v127
	v_mul_f32_e32 v127, v129, v129
	v_mul_f32_e32 v172, v175, v175
	v_fmac_f32_e32 v127, v128, v128
	v_fmac_f32_e32 v172, v174, v174
	v_lshl_add_u64 v[188:189], s[4:5], 0, v[188:189]
	v_add_f32_e32 v127, v127, v172
	v_lshl_add_u64 v[188:189], v[160:161], 1, v[188:189]
	v_add_f32_e32 v172, v126, v127
	v_cvt_pk_bf16_f32 v126, v130, v131
	v_cvt_pk_bf16_f32 v127, v132, v133
	v_pk_add_f32 v[124:125], v[124:125], v[186:187]
	v_pk_add_f32 v[122:123], v[122:123], v[184:185]
	v_cvt_pk_bf16_f32 v128, v128, v129
	v_cvt_pk_bf16_f32 v129, v174, v175
	global_store_dwordx4 v[188:189], v[126:129], off
	s_nop 1
	v_pk_add_f32 v[126:127], v[120:121], v[182:183]
	v_pk_add_f32 v[120:121], v[118:119], v[180:181]
	v_mul_f32_e32 v118, v123, v123
	v_mul_f32_e32 v119, v125, v125
	v_fmac_f32_e32 v118, v122, v122
	v_fmac_f32_e32 v119, v124, v124
	v_add_f32_e32 v118, v118, v119
	v_mul_f32_e32 v119, v121, v121
	v_mul_f32_e32 v128, v127, v127
	v_fmac_f32_e32 v119, v120, v120
	v_fmac_f32_e32 v128, v126, v126
	v_add_f32_e32 v119, v119, v128
	v_add_f32_e32 v118, v118, v119
	v_add_f32_e32 v128, v172, v118
	v_cvt_pk_bf16_f32 v118, v122, v123
	v_cvt_pk_bf16_f32 v119, v124, v125
	v_cvt_pk_bf16_f32 v120, v120, v121
	v_cvt_pk_bf16_f32 v121, v126, v127
	global_store_dwordx4 v[188:189], v[118:121], off offset:256
	s_nop 1
	v_and_b32_e32 v119, 64, v221
	v_xor_b32_e32 v118, 16, v221
	v_add_u32_e32 v119, 64, v119
	v_cmp_lt_i32_e32 vcc, v118, v119
	s_nop 1
	v_cndmask_b32_e32 v118, v221, v118, vcc
	v_lshlrev_b32_e32 v122, 2, v118
	ds_bpermute_b32 v118, v122, v128
	s_waitcnt lgkmcnt(0)
	v_add_f32_e32 v120, v128, v118
	v_xor_b32_e32 v118, 32, v221
	v_cmp_lt_i32_e32 vcc, v118, v119
	s_nop 1
	v_cndmask_b32_e32 v118, v221, v118, vcc
	v_lshlrev_b32_e32 v123, 2, v118
	ds_bpermute_b32 v121, v123, v120
	v_lshl_add_u64 v[118:119], v[162:163], 3, s[18:19]
	s_and_saveexec_b64 s[4:5], s[38:39]
	s_cbranch_execz .LBB0_153
	s_waitcnt lgkmcnt(0)
	v_add_f32_e32 v120, v120, v121
	v_mul_f32_e32 v120, 0x4b800000, v120
	v_trunc_f32_e32 v120, v120
	v_mul_f32_e32 v121, 0x2f800000, v120
	v_floor_f32_e32 v121, v121
	v_fmac_f32_e32 v120, 0xcf800000, v121
	v_cvt_u32_f32_e32 v120, v120
	v_cvt_u32_f32_e32 v121, v121
	global_atomic_add_x2 v[118:119], v[120:121], off
